# v113 + row-scale reductions in the hand-written gu/win epilogues use v_permlane16_swap/v_permlane32_swap instead of two ds_bpermute round trips (bit-identical)
# baseline (speedup 1.0000x reference)
;     DI void operator()(const f32x4 (&acc)[2][2][4][2], const Unit& u, int wr, int wc, int fr, int fq) const {
;     ...
;         const int rowb = u.pm * BM + wr * 64 + fr;
;         f32x4 sl[2][4];
; #pragma unroll
;         for (int ai = 0; ai < 2; ++ai)
; #pragma unroll
;             for (int m = 0; m < 4; ++m) sl[ai][m] = *(const f32x4*)(slots + (size_t)(rowb + ai * HALF + m * 16) * 16 + 4 * fq);
;         asm volatile("" ::: "memory");
; #pragma unroll
;         for (int ai = 0; ai < 2; ++ai) {
;             f32x4 c4[4], s4[4];
; #pragma unroll
;             for (int m = 0; m < 4; ++m) { c4[m] = (f32x4){1.f, 1.f, 1.f, 1.f}; s4[m] = (f32x4){0.f, 0.f, 0.f, 0.f}; }
;             if (rope) {
; #pragma unroll
;                 for (int m = 0; m < 4; ++m) { const int pos = (rowb + ai * HALF + m * 16) & (SEQ - 1); c4[m] = *(const f32x4*)(cs + pos * 64 + fi); s4[m] = *(const f32x4*)(sn + pos * 64 + fi); }
;             }
;             asm volatile("" ::: "memory");
; #pragma unroll
;             for (int m = 0; m < 4; ++m) {
;                 const int row = rowb + ai * HALF + m * 16;
;                 float t = (sl[ai][m][0] + sl[ai][m][1]) + (sl[ai][m][2] + sl[ai][m][3]);
;                 t += __shfl_xor(t, 16); t += __shfl_xor(t, 32);
;                 const float rs = __builtin_amdgcn_rsqf(t * (1.0f / D) + EPS);
.Lwin_fast:
	v_lshl_add_u32 v228, s6, 8, v1
	v_lshl_or_b32 v202, s60, 8, v254
	v_mul_lo_u32 v203, v228, s78
	v_readlane_b32 s101, v255, 24
	v_lshl_add_u32 v138, v202, 1, v203
	v_add_u32_e32 v139, 0x4c000, v138
	v_add_u32_e32 v140, 0x98000, v138
	v_add_u32_e32 v141, 0xe4000, v138
	v_add_u32_e32 v142, 0x260000, v138
	v_add_u32_e32 v143, 0x2ac000, v138
	v_add_u32_e32 v144, 0x2f8000, v138
	v_add_u32_e32 v145, 0x344000, v138
	s_cmp_eq_u32 s101, s6
	s_cbranch_scc1 .Lwin_rs_cached
	v_lshlrev_b32_e32 v224, 6, v228
	v_mov_b32_e32 v225, 0
	v_add_u32_e32 v226, 0x2000, v224
	v_mov_b32_e32 v227, 0
	v_lshl_add_u64 v[224:225], v[214:215], 0, v[224:225]
	v_lshl_add_u64 v[226:227], v[214:215], 0, v[226:227]
	global_load_dwordx4 v[162:165], v[224:225], off
	global_load_dwordx4 v[166:169], v[224:225], off offset:1024
	global_load_dwordx4 v[170:173], v[224:225], off offset:2048
	global_load_dwordx4 v[174:177], v[224:225], off offset:3072
	global_load_dwordx4 v[178:181], v[226:227], off
	global_load_dwordx4 v[182:185], v[226:227], off offset:1024
	global_load_dwordx4 v[186:189], v[226:227], off offset:2048
	global_load_dwordx4 v[190:193], v[226:227], off offset:3072
	v_xor_b32_e32 v200, 16, v249
	v_xor_b32_e32 v201, 32, v249
	v_lshlrev_b32_e32 v200, 2, v200
	v_lshlrev_b32_e32 v201, 2, v201
	v_writelane_b32 v255, s6, 24
	s_waitcnt vmcnt(7)
	v_add_f32_e32 v162, v162, v163
	v_add_f32_e32 v164, v164, v165
	v_add_f32_e32 v162, v162, v164
	v_mov_b32_e32 v163, v162
	s_waitcnt vmcnt(6)
	v_add_f32_e32 v166, v166, v167
	v_add_f32_e32 v168, v168, v169
	v_add_f32_e32 v166, v166, v168
	v_mov_b32_e32 v167, v166
	s_waitcnt vmcnt(5)
	v_add_f32_e32 v170, v170, v171
	v_add_f32_e32 v172, v172, v173
	v_add_f32_e32 v170, v170, v172
	v_mov_b32_e32 v171, v170
	s_waitcnt vmcnt(4)
	v_add_f32_e32 v174, v174, v175
	v_add_f32_e32 v176, v176, v177
	v_add_f32_e32 v174, v174, v176
	v_mov_b32_e32 v175, v174
	s_waitcnt vmcnt(3)
	v_add_f32_e32 v178, v178, v179
	v_add_f32_e32 v180, v180, v181
	v_add_f32_e32 v178, v178, v180
	v_mov_b32_e32 v179, v178
	s_waitcnt vmcnt(2)
	v_add_f32_e32 v182, v182, v183
	v_add_f32_e32 v184, v184, v185
	v_add_f32_e32 v182, v182, v184
	v_mov_b32_e32 v183, v182
	s_waitcnt vmcnt(1)
	v_add_f32_e32 v186, v186, v187
	v_add_f32_e32 v188, v188, v189
	v_add_f32_e32 v186, v186, v188
	v_mov_b32_e32 v187, v186
	s_waitcnt vmcnt(0)
	v_add_f32_e32 v190, v190, v191
	v_add_f32_e32 v192, v192, v193
	v_add_f32_e32 v190, v190, v192
	v_mov_b32_e32 v191, v190
	v_permlane16_swap_b32_e32 v163, v162
	v_permlane16_swap_b32_e32 v167, v166
	v_permlane16_swap_b32_e32 v171, v170
	v_permlane16_swap_b32_e32 v175, v174
	v_permlane16_swap_b32_e32 v179, v178
	v_permlane16_swap_b32_e32 v183, v182
	v_permlane16_swap_b32_e32 v187, v186
	v_permlane16_swap_b32_e32 v191, v190
	v_add_f32_e32 v162, v162, v163
	v_add_f32_e32 v166, v166, v167
	v_add_f32_e32 v170, v170, v171
	v_add_f32_e32 v174, v174, v175
	v_add_f32_e32 v178, v178, v179
	v_add_f32_e32 v182, v182, v183
	v_add_f32_e32 v186, v186, v187
	v_add_f32_e32 v190, v190, v191
	v_mov_b32_e32 v163, v162
	v_mov_b32_e32 v167, v166
	v_mov_b32_e32 v171, v170
	v_mov_b32_e32 v175, v174
	v_mov_b32_e32 v179, v178
	v_mov_b32_e32 v183, v182
	v_mov_b32_e32 v187, v186
	v_mov_b32_e32 v191, v190
	v_permlane32_swap_b32_e32 v163, v162
	v_permlane32_swap_b32_e32 v167, v166
	v_permlane32_swap_b32_e32 v171, v170
	v_permlane32_swap_b32_e32 v175, v174
	v_permlane32_swap_b32_e32 v179, v178
	v_permlane32_swap_b32_e32 v183, v182
	v_permlane32_swap_b32_e32 v187, v186
	v_permlane32_swap_b32_e32 v191, v190
	v_add_f32_e32 v162, v162, v163
	v_add_f32_e32 v166, v166, v167
	v_add_f32_e32 v170, v170, v171
	v_add_f32_e32 v174, v174, v175
	v_add_f32_e32 v178, v178, v179
	v_add_f32_e32 v182, v182, v183
	v_add_f32_e32 v186, v186, v187
	v_add_f32_e32 v190, v190, v191
	v_fmamk_f32 v162, v162, 0x3a800000, v243
	v_fmamk_f32 v166, v166, 0x3a800000, v243
	v_fmamk_f32 v170, v170, 0x3a800000, v243
	v_fmamk_f32 v174, v174, 0x3a800000, v243
	v_fmamk_f32 v178, v178, 0x3a800000, v243
	v_fmamk_f32 v182, v182, 0x3a800000, v243
	v_fmamk_f32 v186, v186, 0x3a800000, v243
	v_fmamk_f32 v190, v190, 0x3a800000, v243
	v_rsq_f32_e32 v204, v162
	v_rsq_f32_e32 v205, v166
	v_rsq_f32_e32 v230, v170
	v_rsq_f32_e32 v231, v174
	v_rsq_f32_e32 v233, v178
	v_rsq_f32_e32 v235, v182
	v_rsq_f32_e32 v240, v186
	v_rsq_f32_e32 v241, v190
	s_nop 1

;     DI void operator()(const f32x4 (&acc)[2][2][4][2], const Unit& u, int wr, int wc, int fr, int fq) const {
;         const int col0 = u.pn * 128 + wc * 32 + 8 * fq;
;         const int rowb = u.pm * BM + wr * 64 + fr;
;         f32x4 sl[2][4];
; #pragma unroll
;         for (int ai = 0; ai < 2; ++ai)
; #pragma unroll
;             for (int m = 0; m < 4; ++m) sl[ai][m] = *(const f32x4*)(slots + (size_t)(rowb + ai * HALF + m * 16) * 16 + 4 * fq);
;         asm volatile("" ::: "memory");
; #pragma unroll
;         for (int ai = 0; ai < 2; ++ai)
; #pragma unroll
;             for (int m = 0; m < 4; ++m) {
;                 const int row = rowb + ai * HALF + m * 16;
;                 float t = (sl[ai][m][0] + sl[ai][m][1]) + (sl[ai][m][2] + sl[ai][m][3]);
;                 t += __shfl_xor(t, 16); t += __shfl_xor(t, 32);
;                 const float rs = __builtin_amdgcn_rsqf(t * (1.0f / D) + EPS);
.LBB0_704:
	v_lshl_add_u32 v178, s54, 8, v1
	v_lshl_or_b32 v179, s17, 7, v185
	v_mul_lo_u32 v166, v178, s92
	v_lshlrev_b32_e32 v179, 1, v179
	s_mov_b32 s98, 0xbfb8aa3b
	s_mov_b32 s100, 1.0
	v_add_u32_e32 v166, v166, v179
	v_add_u32_e32 v167, 0x16000, v166
	v_add_u32_e32 v168, 0x2c000, v166
	v_add_u32_e32 v169, 0x42000, v166
	v_add_u32_e32 v170, 0xb0000, v166
	v_add_u32_e32 v171, 0xc6000, v166
	v_add_u32_e32 v172, 0xdc000, v166
	v_add_u32_e32 v173, 0xf2000, v166
	s_cmp_eq_u32 s99, s54
	s_cbranch_scc1 .Lgu_rs_cached
	v_lshlrev_b32_e32 v102, 6, v178
	v_mov_b32_e32 v103, 0
	v_add_u32_e32 v104, 0x2000, v102
	v_mov_b32_e32 v105, 0
	v_lshl_add_u64 v[102:103], v[160:161], 0, v[102:103]
	v_lshl_add_u64 v[104:105], v[160:161], 0, v[104:105]
	global_load_dwordx4 v[206:209], v[102:103], off
	global_load_dwordx4 v[210:213], v[102:103], off offset:1024
	global_load_dwordx4 v[214:217], v[102:103], off offset:2048
	global_load_dwordx4 v[218:221], v[102:103], off offset:3072
	global_load_dwordx4 v[222:225], v[104:105], off
	global_load_dwordx4 v[200:203], v[104:105], off offset:1024
	global_load_dwordx4 v[188:191], v[104:105], off offset:2048
	global_load_dwordx4 v[140:143], v[104:105], off offset:3072
	v_xor_b32_e32 v204, 16, v249
	v_xor_b32_e32 v205, 32, v249
	v_lshlrev_b32_e32 v204, 2, v204
	v_lshlrev_b32_e32 v205, 2, v205
	s_mov_b32 s99, s54
	s_waitcnt vmcnt(7)
	v_add_f32_e32 v206, v206, v207
	v_add_f32_e32 v208, v208, v209
	v_add_f32_e32 v206, v206, v208
	v_mov_b32_e32 v207, v206
	s_waitcnt vmcnt(6)
	v_add_f32_e32 v210, v210, v211
	v_add_f32_e32 v212, v212, v213
	v_add_f32_e32 v210, v210, v212
	v_mov_b32_e32 v211, v210
	s_waitcnt vmcnt(5)
	v_add_f32_e32 v214, v214, v215
	v_add_f32_e32 v216, v216, v217
	v_add_f32_e32 v214, v214, v216
	v_mov_b32_e32 v215, v214
	s_waitcnt vmcnt(4)
	v_add_f32_e32 v218, v218, v219
	v_add_f32_e32 v220, v220, v221
	v_add_f32_e32 v218, v218, v220
	v_mov_b32_e32 v219, v218
	s_waitcnt vmcnt(3)
	v_add_f32_e32 v222, v222, v223
	v_add_f32_e32 v224, v224, v225
	v_add_f32_e32 v222, v222, v224
	v_mov_b32_e32 v223, v222
	s_waitcnt vmcnt(2)
	v_add_f32_e32 v200, v200, v201
	v_add_f32_e32 v202, v202, v203
	v_add_f32_e32 v200, v200, v202
	v_mov_b32_e32 v201, v200
	s_waitcnt vmcnt(1)
	v_add_f32_e32 v188, v188, v189
	v_add_f32_e32 v190, v190, v191
	v_add_f32_e32 v188, v188, v190
	v_mov_b32_e32 v189, v188
	s_waitcnt vmcnt(0)
	v_add_f32_e32 v140, v140, v141
	v_add_f32_e32 v142, v142, v143
	v_add_f32_e32 v140, v140, v142
	v_mov_b32_e32 v141, v140
	v_permlane16_swap_b32_e32 v207, v206
	v_permlane16_swap_b32_e32 v211, v210
	v_permlane16_swap_b32_e32 v215, v214
	v_permlane16_swap_b32_e32 v219, v218
	v_permlane16_swap_b32_e32 v223, v222
	v_permlane16_swap_b32_e32 v201, v200
	v_permlane16_swap_b32_e32 v189, v188
	v_permlane16_swap_b32_e32 v141, v140
	v_add_f32_e32 v206, v206, v207
	v_add_f32_e32 v210, v210, v211
	v_add_f32_e32 v214, v214, v215
	v_add_f32_e32 v218, v218, v219
	v_add_f32_e32 v222, v222, v223
	v_add_f32_e32 v200, v200, v201
	v_add_f32_e32 v188, v188, v189
	v_add_f32_e32 v140, v140, v141
	v_mov_b32_e32 v207, v206
	v_mov_b32_e32 v211, v210
	v_mov_b32_e32 v215, v214
	v_mov_b32_e32 v219, v218
	v_mov_b32_e32 v223, v222
	v_mov_b32_e32 v201, v200
	v_mov_b32_e32 v189, v188
	v_mov_b32_e32 v141, v140
	v_permlane32_swap_b32_e32 v207, v206
	v_permlane32_swap_b32_e32 v211, v210
	v_permlane32_swap_b32_e32 v215, v214
	v_permlane32_swap_b32_e32 v219, v218
	v_permlane32_swap_b32_e32 v223, v222
	v_permlane32_swap_b32_e32 v201, v200
	v_permlane32_swap_b32_e32 v189, v188
	v_permlane32_swap_b32_e32 v141, v140
	v_add_f32_e32 v206, v206, v207
	v_add_f32_e32 v210, v210, v211
	v_add_f32_e32 v214, v214, v215
	v_add_f32_e32 v218, v218, v219
	v_add_f32_e32 v222, v222, v223
	v_add_f32_e32 v200, v200, v201
	v_add_f32_e32 v188, v188, v189
	v_add_f32_e32 v140, v140, v141
	v_fmamk_f32 v206, v206, 0x3a800000, v243
	v_fmamk_f32 v210, v210, 0x3a800000, v243
	v_fmamk_f32 v214, v214, 0x3a800000, v243
	v_fmamk_f32 v218, v218, 0x3a800000, v243
	v_fmamk_f32 v222, v222, 0x3a800000, v243
	v_fmamk_f32 v200, v200, 0x3a800000, v243
	v_fmamk_f32 v188, v188, 0x3a800000, v243
	v_fmamk_f32 v140, v140, 0x3a800000, v243
	v_rsq_f32_e32 v232, v206
	v_rsq_f32_e32 v233, v210
	v_rsq_f32_e32 v234, v214
	v_rsq_f32_e32 v235, v218
	v_rsq_f32_e32 v236, v222
	v_rsq_f32_e32 v237, v200
	v_rsq_f32_e32 v238, v188
	v_rsq_f32_e32 v239, v140
	s_nop 1
